# P1 row-scale table fill: unit row blocks computed on the SALU and both RS loads of a thread issued together (was a per-iteration load+wait loop)
# speedup vs baseline: 1.0024x; 1.0024x over previous
.LBB0_306:
	s_and_b32 s60, s2, 7
	s_mul_i32 s60, s60, 0x60
	s_lshr_b32 s61, s2, 3
	s_add_i32 s60, s60, s61
	v_readfirstlane_b32 s61, v208
	s_lshr_b32 s61, s61, 8
	s_lshl_b32 s62, s61, 5
	s_add_i32 s62, s60, s62
	s_mul_hi_u32 s65, s62, 0x1555556
	s_mul_i32 s66, s65, 0xc0
	s_sub_i32 s66, s62, s66
	s_and_b32 s66, s66, 7
	s_lshl_b32 s65, s65, 3
	s_add_i32 s63, s65, s66
	s_add_i32 s62, s60, 64
	s_mul_hi_u32 s65, s62, 0x1555556
	s_mul_i32 s66, s65, 0xc0
	s_sub_i32 s66, s62, s66
	s_and_b32 s66, s66, 7
	s_lshl_b32 s65, s65, 3
	s_add_i32 s64, s65, s66
	v_and_b32_e32 v0, 0xff, v208
	v_lshlrev_b32_e32 v0, 2, v0
	s_lshl_b32 s66, s63, 10
	s_add_u32 s66, s4, s66
	s_addc_u32 s67, s5, 0
	global_load_dword v1, v0, s[66:67]
	s_cmp_eq_u32 s61, 0
	s_cbranch_scc0 .Lmy_rx_one
	s_lshl_b32 s66, s64, 10
	s_add_u32 s66, s4, s66
	s_addc_u32 s67, s5, 0
	global_load_dword v2, v0, s[66:67]
	s_waitcnt vmcnt(0)
	ds_write_b32 v4, v1
	ds_write_b32 v4, v2 offset:2048
	s_branch .Lmy_rx_done
.Lmy_rx_one:
	s_waitcnt vmcnt(0)
	ds_write_b32 v4, v1
.Lmy_rx_done:
	s_mov_b64 s[36:37], 0
